# claim loops of the conversion tails (P1,P15,P17) pipelined: next claim prefetched right after the current one is validated; stacked on staged rstd tables + zeroing peel + SWA prologue fix
# baseline (speedup 1.0000x reference)
.LBB0_255:
	s_add_u32 s6, s18, 0xc000
	s_addc_u32 s7, s19, 0
	s_add_i32 s2, 0, 0x27c30
	v_mov_b32_e32 v69, 0
	v_mov_b32_e32 v86, s2
	s_movk_i32 s20, 0x5600
	s_mov_b32 s21, 0xb002300
	s_mov_b32 s26, 0xc3e00000
	v_mov_b32_e32 v87, 0x46000000
	v_mov_b32_e32 v88, 0x44800000
	v_lshlrev_b32_e32 v68, 2, v1
	v_mov_b32_e32 v89, 0x43e00000
	s_mov_b32 s27, 0
	s_and_saveexec_b64 s[100:101], s[94:95]
	s_cbranch_execz .Lclaimfirst_0
	s_add_u32 s98, s18, 0xc000
	s_addc_u32 s99, s19, 0
	v_mov_b32_e32 v254, 0
	v_mov_b32_e32 v255, 1
	global_atomic_add v255, v254, v255, s[98:99] sc0
.Lclaimfirst_0:
	s_or_b64 exec, exec, s[100:101]
	s_branch .LBB0_258

.LBB0_258:
	s_waitcnt vmcnt(0)
	s_barrier
	s_and_saveexec_b64 s[10:11], s[94:95]
	s_cbranch_execz .LBB0_262
	s_mov_b64 s[22:23], exec
	v_mbcnt_lo_u32_b32 v2, s22, 0
	v_mbcnt_hi_u32_b32 v2, s23, v2
	v_cmp_eq_u32_e32 vcc, 0, v2
	s_and_saveexec_b64 s[14:15], vcc
	s_cbranch_execz .LBB0_261
	s_bcnt1_i32_b64 s4, s[22:23]
	v_mov_b32_e32 v3, s4
	v_mov_b32_e32 v3, v255

.LBB0_262:
	s_or_b64 exec, exec, s[10:11]
	s_waitcnt lgkmcnt(0)
	s_barrier
	ds_read_b32 v2, v86
	s_mov_b64 s[10:11], -1
	s_waitcnt lgkmcnt(0)
	v_readfirstlane_b32 s38, v2
	s_cmpk_gt_i32 s38, 0x2af
	s_cbranch_scc1 .LBB0_257
	s_and_saveexec_b64 s[100:101], s[94:95]
	s_cbranch_execz .Lclaimnx_0
	s_add_u32 s98, s18, 0xc000
	s_addc_u32 s99, s19, 0
	v_mov_b32_e32 v254, 0
	v_mov_b32_e32 v255, 1
	global_atomic_add v255, v254, v255, s[98:99] sc0
.Lclaimnx_0:
	s_or_b64 exec, exec, s[100:101]
	s_add_i32 s24, s38, 0x2b0
	s_cmp_gt_i32 s38, -1
	s_cbranch_scc0 .LBB0_268
	s_add_i32 s4, s24, 0xfd50
	s_and_b32 s10, s4, 0xffff
	s_mul_i32 s10, s10, 0xbe83
	s_lshr_b32 s14, s10, 21
	s_mul_i32 s10, s14, 43
	s_sub_i32 s4, s4, s10
	s_lshl_b32 s10, s4, 2
	s_lshl_b32 s14, s14, 8
	s_and_b32 s39, s10, 0xfffc
	s_add_i32 s36, s14, s29
	s_and_b32 s4, s4, 0xffff
	s_cmp_gt_u32 s4, 34
	s_load_dwordx2 s[10:11], s[0:1], 0x30
	s_cselect_b64 vcc, -1, 0
	s_and_b64 s[14:15], vcc, exec
	s_cselect_b32 s14, s21, 0xb000000
	s_cselect_b32 s4, s20, 0x2b00
	s_add_u32 s30, s18, s14
	v_cndmask_b32_e64 v91, v87, 1.0, vcc
	v_cndmask_b32_e32 v90, 0, v88, vcc
	s_addc_u32 s31, s19, 0
	s_cbranch_execz .LBB0_269
	s_mov_b64 s[22:23], 0
	s_movk_i32 s24, 0x1000
	s_mov_b32 s52, 4
	s_mov_b32 s14, s36
	s_lshl_b32 s46, s39, 6
	s_cmp_lt_i32 s14, 0
	s_cbranch_scc0 .LBB0_270

.LBB0_1957:
	s_add_i32 s2, 0, 0x27c30
	s_mov_b32 s5, 0
	v_mov_b32_e32 v69, 0
	v_mov_b32_e32 v86, s2
	s_movk_i32 s20, 0x2b0
	s_mov_b32 s21, 0x23000000
	s_movk_i32 s26, 0xf9c4
	s_movk_i32 s27, 0xdc0
	s_movk_i32 s38, 0x5600
	s_mov_b32 s39, 0xb002300
	s_mov_b32 s62, 0xc3e00000
	v_mov_b32_e32 v87, 0x46000000
	v_mov_b32_e32 v88, 0x44800000
	v_lshlrev_b32_e32 v68, 2, v1
	v_mov_b32_e32 v89, 0x43e00000
	s_mov_b32 s63, 0
	s_and_saveexec_b64 s[100:101], s[94:95]
	s_cbranch_execz .Lclaimfirst_1
	s_add_u32 s98, s18, 0xc200
	s_addc_u32 s99, s19, 0
	v_mov_b32_e32 v254, 0
	v_mov_b32_e32 v255, 1
	global_atomic_add v255, v254, v255, s[98:99] sc0

.LBB0_1960:
	s_waitcnt vmcnt(0) lgkmcnt(0)
	s_barrier
	s_and_saveexec_b64 s[6:7], s[94:95]
	s_cbranch_execz .LBB0_1964
	s_mov_b64 s[24:25], exec
	v_mbcnt_lo_u32_b32 v2, s24, 0
	v_mbcnt_hi_u32_b32 v2, s25, v2
	v_cmp_eq_u32_e32 vcc, 0, v2
	s_and_saveexec_b64 s[22:23], vcc
	s_cbranch_execz .LBB0_1963
	s_bcnt1_i32_b64 s4, s[24:25]
	v_readlane_b32 s14, v250, 33
	v_mov_b32_e32 v3, s4
	v_readlane_b32 s15, v250, 34
	s_nop 4
	v_mov_b32_e32 v3, v255

.LBB0_1964:
	s_or_b64 exec, exec, s[6:7]
	s_waitcnt lgkmcnt(0)
	s_barrier
	ds_read_b32 v2, v86
	s_mov_b64 s[6:7], -1
	s_waitcnt lgkmcnt(0)
	v_readfirstlane_b32 s64, v2
	s_cmpk_gt_i32 s64, 0x9b3
	s_cbranch_scc1 .LBB0_1959
	s_and_saveexec_b64 s[100:101], s[94:95]
	s_cbranch_execz .Lclaimnx_1
	s_add_u32 s98, s18, 0xc200
	s_addc_u32 s99, s19, 0
	v_mov_b32_e32 v254, 0
	v_mov_b32_e32 v255, 1
	global_atomic_add v255, v254, v255, s[98:99] sc0
.Lclaimnx_1:
	s_or_b64 exec, exec, s[100:101]
	s_cmpk_lt_i32 s64, 0x454
	s_cselect_b32 s4, s20, 0xfffffbac
	s_cmpk_lt_i32 s64, 0x704
	s_cselect_b32 s33, s4, 0
	s_add_i32 s33, s33, s64
	s_cmpk_lt_i32 s33, 0x704
	s_cbranch_scc0 .LBB0_1977
	s_cmpk_gt_i32 s33, 0x2af
	s_cbranch_scc0 .LBB0_2056
	s_cmpk_gt_u32 s33, 0x55f
	s_mov_b64 s[52:53], -1
	s_cbranch_scc0 .LBB0_2100
	s_cmpk_gt_u32 s33, 0x5df
	s_cbranch_scc0 .LBB0_2084
	s_cmpk_gt_u32 s33, 0x633
	s_cbranch_scc0 .LBB0_2081
	s_cmpk_gt_u32 s33, 0x643
	s_cbranch_scc0 .LBB0_2078
	s_cmpk_gt_u32 s33, 0x6c3
	s_cbranch_scc0 .LBB0_2071
	s_cmpk_gt_u32 s33, 0x6d3
	s_mov_b64 s[30:31], -1
	s_cbranch_scc0 .LBB0_2069
	s_cmpk_gt_u32 s33, 0x6f3
	s_mov_b64 s[24:25], -1
	s_cbranch_scc0 .LBB0_1975
	s_load_dwordx2 s[6:7], s[0:1], 0xd8
	s_lshl_b32 s4, s33, 8
	s_add_i32 s22, s4, s97
	s_mov_b64 s[24:25], 0

.LBB0_2178:
	s_add_u32 s4, s18, 0xc100
	v_readlane_b32 s8, v250, 35
	s_addc_u32 s5, s19, 0
	v_readlane_b32 s9, v250, 36
	s_movk_i32 s2, 0xab4
	s_and_b64 s[8:9], s[8:9], exec
	s_cselect_b32 s2, s2, 0x9b4
	s_add_i32 s20, 0, 0x27c30
	s_mov_b32 s9, 0
	v_mov_b32_e32 v69, 0
	v_mov_b32_e32 v86, s20
	s_movk_i32 s21, 0x2b0
	s_mov_b32 s26, 0x23000000
	s_movk_i32 s27, 0xf9c4
	s_movk_i32 s38, 0xdc0
	s_movk_i32 s39, 0x5600
	s_mov_b32 s60, 0xb002300
	s_mov_b32 s61, 0xc3e00000
	v_mov_b32_e32 v87, 0x46000000
	v_mov_b32_e32 v88, 0x44800000
	v_lshlrev_b32_e32 v68, 2, v1
	v_mov_b32_e32 v89, 0x43e00000
	s_mov_b32 s62, 0
	s_and_saveexec_b64 s[100:101], s[94:95]
	s_cbranch_execz .Lclaimfirst_2
	s_add_u32 s98, s18, 0xc100
	s_addc_u32 s99, s19, 0
	v_mov_b32_e32 v254, 0
	v_mov_b32_e32 v255, 1
	global_atomic_add v255, v254, v255, s[98:99] sc0

.LBB0_2181:
	s_waitcnt vmcnt(0)
	s_barrier
	s_and_saveexec_b64 s[14:15], s[94:95]
	s_cbranch_execz .LBB0_2185
	s_mov_b64 s[24:25], exec
	v_mbcnt_lo_u32_b32 v2, s24, 0
	v_mbcnt_hi_u32_b32 v2, s25, v2
	v_cmp_eq_u32_e32 vcc, 0, v2
	s_and_saveexec_b64 s[22:23], vcc
	s_cbranch_execz .LBB0_2184
	s_bcnt1_i32_b64 s8, s[24:25]
	v_mov_b32_e32 v3, s8
	v_mov_b32_e32 v3, v255

.LBB0_2185:
	s_or_b64 exec, exec, s[14:15]
	s_waitcnt lgkmcnt(0)
	s_barrier
	ds_read_b32 v2, v86
	s_mov_b64 s[14:15], -1
	s_waitcnt lgkmcnt(0)
	v_readfirstlane_b32 s63, v2
	s_cmpk_gt_i32 s63, 0xc63
	s_cbranch_scc1 .LBB0_2180
	s_and_saveexec_b64 s[100:101], s[94:95]
	s_cbranch_execz .Lclaimnx_2
	s_add_u32 s98, s18, 0xc100
	s_addc_u32 s99, s19, 0
	v_mov_b32_e32 v254, 0
	v_mov_b32_e32 v255, 1
	global_atomic_add v255, v254, v255, s[98:99] sc0
.Lclaimnx_2:
	s_or_b64 exec, exec, s[100:101]
	s_cmpk_lt_i32 s63, 0x454
	s_cselect_b32 s8, s21, 0xfffffbac
	s_cmpk_lt_i32 s63, 0x704
	s_cselect_b32 s36, s8, 0
	s_add_i32 s36, s36, s63
	s_cmpk_lt_i32 s36, 0x704
	s_cbranch_scc0 .LBB0_2198
	s_cmpk_gt_i32 s36, 0x2af
	s_cbranch_scc0 .LBB0_2277
	s_cmpk_gt_u32 s36, 0x55f
	s_mov_b64 s[50:51], -1
	s_cbranch_scc0 .LBB0_2321
	s_cmpk_gt_u32 s36, 0x5df
	s_cbranch_scc0 .LBB0_2305
	s_cmpk_gt_u32 s36, 0x633
	s_cbranch_scc0 .LBB0_2302
	s_cmpk_gt_u32 s36, 0x643
	s_cbranch_scc0 .LBB0_2299
	s_cmpk_gt_u32 s36, 0x6c3
	s_cbranch_scc0 .LBB0_2292
	s_cmpk_gt_u32 s36, 0x6d3
	s_mov_b64 s[30:31], -1
	s_cbranch_scc0 .LBB0_2290
	s_cmpk_gt_u32 s36, 0x6f3
	s_mov_b64 s[24:25], -1
	s_cbranch_scc0 .LBB0_2196
	s_load_dwordx2 s[14:15], s[0:1], 0xd8
	s_lshl_b32 s8, s36, 8
	s_add_i32 s22, s8, s97
	s_mov_b64 s[24:25], 0

	.amdhsa_kernel _Z10fwd_kernel4Args
		.amdhsa_group_segment_fixed_size 0
		.amdhsa_private_segment_fixed_size 0
		.amdhsa_kernarg_size 536
		.amdhsa_user_sgpr_count 2
		.amdhsa_user_sgpr_dispatch_ptr 0
		.amdhsa_user_sgpr_queue_ptr 0
		.amdhsa_user_sgpr_kernarg_segment_ptr 1
		.amdhsa_user_sgpr_dispatch_id 0
		.amdhsa_user_sgpr_kernarg_preload_length 0
		.amdhsa_user_sgpr_kernarg_preload_offset 0
		.amdhsa_user_sgpr_private_segment_size 0
		.amdhsa_uses_dynamic_stack 0
		.amdhsa_enable_private_segment 0
		.amdhsa_system_sgpr_workgroup_id_x 1
		.amdhsa_system_sgpr_workgroup_id_y 0
		.amdhsa_system_sgpr_workgroup_id_z 0
		.amdhsa_system_sgpr_workgroup_info 0
		.amdhsa_system_vgpr_workitem_id 0
		.amdhsa_next_free_vgpr 256
		.amdhsa_next_free_sgpr 102
		.amdhsa_accum_offset 256
		.amdhsa_reserve_vcc 1
		.amdhsa_float_round_mode_32 0
		.amdhsa_float_round_mode_16_64 0
		.amdhsa_float_denorm_mode_32 3
		.amdhsa_float_denorm_mode_16_64 3
		.amdhsa_dx10_clamp 1
		.amdhsa_ieee_mode 1
		.amdhsa_fp16_overflow 0
		.amdhsa_tg_split 0
		.amdhsa_exception_fp_ieee_invalid_op 0
		.amdhsa_exception_fp_denorm_src 0
		.amdhsa_exception_fp_ieee_div_zero 0
		.amdhsa_exception_fp_ieee_overflow 0
		.amdhsa_exception_fp_ieee_underflow 0
		.amdhsa_exception_fp_ieee_inexact 0
		.amdhsa_exception_int_div_zero 0
	.end_amdhsa_kernel

amdhsa.kernels:
  - .agpr_count:     0
    .args:
      - .offset:         0
        .size:           280
        .value_kind:     by_value
      - .offset:         280
        .size:           4
        .value_kind:     hidden_block_count_x
      - .offset:         284
        .size:           4
        .value_kind:     hidden_block_count_y
      - .offset:         288
        .size:           4
        .value_kind:     hidden_block_count_z
      - .offset:         292
        .size:           2
        .value_kind:     hidden_group_size_x
      - .offset:         294
        .size:           2
        .value_kind:     hidden_group_size_y
      - .offset:         296
        .size:           2
        .value_kind:     hidden_group_size_z
      - .offset:         298
        .size:           2
        .value_kind:     hidden_remainder_x
      - .offset:         300
        .size:           2
        .value_kind:     hidden_remainder_y
      - .offset:         302
        .size:           2
        .value_kind:     hidden_remainder_z
      - .offset:         320
        .size:           8
        .value_kind:     hidden_global_offset_x
      - .offset:         328
        .size:           8
        .value_kind:     hidden_global_offset_y
      - .offset:         336
        .size:           8
        .value_kind:     hidden_global_offset_z
      - .offset:         344
        .size:           2
        .value_kind:     hidden_grid_dims
      - .offset:         400
        .size:           4
        .value_kind:     hidden_dynamic_lds_size
    .group_segment_fixed_size: 0
    .kernarg_segment_align: 8
    .kernarg_segment_size: 536
    .language:       OpenCL C
    .language_version:
      - 2
      - 0
    .max_flat_workgroup_size: 512
    .name:           _Z10fwd_kernel4Args
    .private_segment_fixed_size: 0
    .sgpr_count:     108
    .sgpr_spill_count: 58
    .symbol:         _Z10fwd_kernel4Args.kd
    .uniform_work_group_size: 1
    .uses_dynamic_stack: false
    .vgpr_count:     256
    .vgpr_spill_count: 0
    .wavefront_size: 64
